# attention mid-step barrier: bias init and address toggles moved ahead of the barrier, K-fragment reads lead the segment after it
# speedup vs baseline: 1.0151x; 1.0020x over previous
.Lat_nre:
	v_xor_b32_e32 v186, 0x80, v186
	v_xor_b32_e32 v187, 0x80, v187
	v_xor_b32_e32 v188, 0x80, v188
	v_xor_b32_e32 v189, 0x80, v189
	v_cvt_f32_u32_e32 v204, s13
	v_mov_b32_e32 v165, v164
	v_fma_f32 v204, v172, v204, v179
	v_add_f32_e32 v208, v173, v204
	v_add_f32_e32 v212, v173, v208
	v_add_f32_e32 v216, v173, v212
	v_add_f32_e32 v205, v172, v204
	v_add_f32_e32 v209, v172, v208
	v_add_f32_e32 v213, v172, v212
	v_add_f32_e32 v217, v172, v216
	v_pk_add_f32 v[206:207], v[162:163], v[204:205] op_sel_hi:[1,0]
	v_pk_add_f32 v[210:211], v[162:163], v[208:209] op_sel_hi:[1,0]
	v_pk_add_f32 v[214:215], v[162:163], v[212:213] op_sel_hi:[1,0]
	v_pk_add_f32 v[218:219], v[162:163], v[216:217] op_sel_hi:[1,0]
	v_pk_add_f32 v[222:223], v[164:165], v[206:207]
	v_pk_add_f32 v[220:221], v[166:167], v[204:205]
	v_pk_add_f32 v[226:227], v[164:165], v[210:211]
	v_pk_add_f32 v[224:225], v[164:165], v[208:209]
	v_pk_add_f32 v[230:231], v[164:165], v[214:215]
	v_pk_add_f32 v[228:229], v[164:165], v[212:213]
	v_pk_add_f32 v[234:235], v[164:165], v[218:219]
	v_pk_add_f32 v[232:233], v[164:165], v[216:217]
	s_addk_i32 s13, 0x40
	s_waitcnt lgkmcnt(0)
	s_barrier
	ds_read_b128 v[236:239], v186 offset:49152
	ds_read_b128 v[240:243], v186 offset:57344
	v_exp_f32_e32 v80, v80
	s_waitcnt lgkmcnt(1)
	v_mfma_f32_32x32x16_bf16 v[204:219], v[236:239], v[104:107], v[204:219]
	ds_read_b128 v[236:239], v187 offset:49152
	v_exp_f32_e32 v81, v81
	v_pk_add_f32 v[170:171], v[170:171], v[78:79]
	v_exp_f32_e32 v82, v82
	s_waitcnt lgkmcnt(1)
	v_mfma_f32_32x32x16_bf16 v[220:235], v[240:243], v[104:107], v[220:235]
	ds_read_b128 v[240:243], v187 offset:57344
	v_exp_f32_e32 v83, v83
	v_pk_add_f32 v[170:171], v[170:171], v[80:81]
	v_exp_f32_e32 v84, v84
	v_exp_f32_e32 v85, v85
	s_waitcnt lgkmcnt(1)
	v_mfma_f32_32x32x16_bf16 v[204:219], v[236:239], v[108:111], v[204:219]
	ds_read_b128 v[236:239], v188 offset:49152
	v_pk_add_f32 v[170:171], v[170:171], v[82:83]
	v_exp_f32_e32 v86, v86
	v_exp_f32_e32 v87, v87
	s_waitcnt lgkmcnt(1)
	v_mfma_f32_32x32x16_bf16 v[220:235], v[240:243], v[108:111], v[220:235]
	ds_read_b128 v[240:243], v188 offset:57344
	v_pk_add_f32 v[170:171], v[170:171], v[84:85]
	v_exp_f32_e32 v88, v88
	v_exp_f32_e32 v89, v89
	v_pk_add_f32 v[170:171], v[170:171], v[86:87]
	s_waitcnt lgkmcnt(1)
	v_mfma_f32_32x32x16_bf16 v[204:219], v[236:239], v[112:115], v[204:219]
	ds_read_b128 v[236:239], v189 offset:49152
	v_exp_f32_e32 v90, v90
	v_exp_f32_e32 v91, v91
	v_pk_add_f32 v[170:171], v[170:171], v[88:89]
	v_exp_f32_e32 v92, v92
	s_waitcnt lgkmcnt(1)
	v_mfma_f32_32x32x16_bf16 v[220:235], v[240:243], v[112:115], v[220:235]
	ds_read_b128 v[240:243], v189 offset:57344
	v_exp_f32_e32 v93, v93
	v_pk_add_f32 v[170:171], v[170:171], v[90:91]
	v_exp_f32_e32 v94, v94
	s_waitcnt lgkmcnt(1)
	v_mfma_f32_32x32x16_bf16 v[204:219], v[236:239], v[116:119], v[204:219]
	v_xor_b32_e32 v186, 0x80, v186
	v_xor_b32_e32 v187, 0x80, v187
	v_xor_b32_e32 v188, 0x80, v188
	v_xor_b32_e32 v189, 0x80, v189
	ds_read_b128 v[236:239], v186 offset:49152
	v_exp_f32_e32 v95, v95
	v_pk_add_f32 v[170:171], v[170:171], v[92:93]
	s_nop 0
	v_pk_add_f32 v[170:171], v[170:171], v[94:95]
	s_waitcnt lgkmcnt(1)
	v_mfma_f32_32x32x16_bf16 v[220:235], v[240:243], v[116:119], v[220:235]
	ds_read_b128 v[240:243], v186 offset:57344
	v_add_f32_e32 v249, v170, v171
	v_mov_b32_e32 v170, v249
	s_nop 1
	s_waitcnt lgkmcnt(1)
	v_mfma_f32_32x32x16_bf16 v[204:219], v[236:239], v[120:123], v[204:219]
	ds_read_b128 v[236:239], v187 offset:49152
	v_permlane32_swap_b32_e32 v249, v170
	v_cvt_pk_bf16_f32 v64, v64, v65
	v_cvt_pk_bf16_f32 v65, v66, v67
	v_cvt_pk_bf16_f32 v66, v68, v69
	s_waitcnt lgkmcnt(1)
	v_mfma_f32_32x32x16_bf16 v[220:235], v[240:243], v[120:123], v[220:235]
	ds_read_b128 v[240:243], v187 offset:57344
	v_cvt_pk_bf16_f32 v67, v70, v71
	v_cvt_pk_bf16_f32 v68, v72, v73
	v_cvt_pk_bf16_f32 v69, v74, v75
	s_waitcnt lgkmcnt(1)
	v_mfma_f32_32x32x16_bf16 v[204:219], v[236:239], v[124:127], v[204:219]
	ds_read_b128 v[236:239], v188 offset:49152
	v_cvt_pk_bf16_f32 v70, v76, v77
	v_cvt_pk_bf16_f32 v71, v78, v79
	v_cvt_pk_bf16_f32 v72, v80, v81
	v_cvt_pk_bf16_f32 v73, v82, v83
	s_waitcnt lgkmcnt(1)
	v_mfma_f32_32x32x16_bf16 v[220:235], v[240:243], v[124:127], v[220:235]
	ds_read_b128 v[240:243], v188 offset:57344
	v_cvt_pk_bf16_f32 v74, v84, v85
	v_cvt_pk_bf16_f32 v75, v86, v87
	v_cvt_pk_bf16_f32 v76, v88, v89
	s_waitcnt lgkmcnt(1)
	v_mfma_f32_32x32x16_bf16 v[204:219], v[236:239], v[128:131], v[204:219]
	ds_read_b128 v[236:239], v189 offset:49152
	v_cvt_pk_bf16_f32 v77, v90, v91
	v_cvt_pk_bf16_f32 v78, v92, v93
	v_cvt_pk_bf16_f32 v79, v94, v95
	v_permlane32_swap_b32_e32 v64, v66
	s_waitcnt lgkmcnt(1)
	v_mfma_f32_32x32x16_bf16 v[220:235], v[240:243], v[128:131], v[220:235]
	ds_read_b128 v[240:243], v189 offset:57344
	v_permlane32_swap_b32_e32 v65, v67
	v_permlane32_swap_b32_e32 v68, v70
	v_permlane32_swap_b32_e32 v69, v71
	v_permlane32_swap_b32_e32 v72, v74
	s_waitcnt lgkmcnt(1)
	v_mfma_f32_32x32x16_bf16 v[204:219], v[236:239], v[132:135], v[204:219]
	v_permlane32_swap_b32_e32 v73, v75
	v_permlane32_swap_b32_e32 v76, v78
	v_permlane32_swap_b32_e32 v77, v79
	s_waitcnt lgkmcnt(0)
	v_mfma_f32_32x32x16_bf16 v[220:235], v[240:243], v[132:135], v[220:235]
	v_add_f32_e32 v171, v249, v170
	v_fmac_f32_e32 v171, v185, v202
	v_mov_b32_e32 v185, v171
	s_waitcnt vmcnt(0)
	v_add_u32_e32 v200, s8, v180
	v_add_u32_e32 v201, s8, v181
	ds_write_b128 v200, v[96:99]
	ds_write_b128 v201, v[100:103]
	s_and_b64 vcc, exec, s[34:35]
	s_cbranch_vccz .Lat_nwe
	ds_write_b128 v182, v[136:139] offset:32768
	ds_write_b128 v182, v[140:143] offset:40960

.Lat_nro:
	v_xor_b32_e32 v186, 0x80, v186
	v_xor_b32_e32 v187, 0x80, v187
	v_xor_b32_e32 v188, 0x80, v188
	v_xor_b32_e32 v189, 0x80, v189
	v_cvt_f32_u32_e32 v64, s13
	v_mov_b32_e32 v165, v164
	v_fma_f32 v64, v172, v64, v179
	v_add_f32_e32 v68, v173, v64
	v_add_f32_e32 v72, v173, v68
	v_add_f32_e32 v76, v173, v72
	v_add_f32_e32 v65, v172, v64
	v_add_f32_e32 v69, v172, v68
	v_add_f32_e32 v73, v172, v72
	v_add_f32_e32 v77, v172, v76
	v_pk_add_f32 v[66:67], v[162:163], v[64:65] op_sel_hi:[1,0]
	v_pk_add_f32 v[70:71], v[162:163], v[68:69] op_sel_hi:[1,0]
	v_pk_add_f32 v[74:75], v[162:163], v[72:73] op_sel_hi:[1,0]
	v_pk_add_f32 v[78:79], v[162:163], v[76:77] op_sel_hi:[1,0]
	v_pk_add_f32 v[82:83], v[164:165], v[66:67]
	v_pk_add_f32 v[80:81], v[166:167], v[64:65]
	v_pk_add_f32 v[86:87], v[164:165], v[70:71]
	v_pk_add_f32 v[84:85], v[164:165], v[68:69]
	v_pk_add_f32 v[90:91], v[164:165], v[74:75]
	v_pk_add_f32 v[88:89], v[164:165], v[72:73]
	v_pk_add_f32 v[94:95], v[164:165], v[78:79]
	v_pk_add_f32 v[92:93], v[164:165], v[76:77]
	s_addk_i32 s13, 0x40
	s_waitcnt lgkmcnt(0)
	s_barrier
	ds_read_b128 v[236:239], v186 offset:32768
	ds_read_b128 v[240:243], v186 offset:40960
	v_exp_f32_e32 v220, v220
	s_waitcnt lgkmcnt(1)
	v_mfma_f32_32x32x16_bf16 v[64:79], v[236:239], v[104:107], v[64:79]
	ds_read_b128 v[236:239], v187 offset:32768
	v_exp_f32_e32 v221, v221
	v_pk_add_f32 v[170:171], v[170:171], v[218:219]
	v_exp_f32_e32 v222, v222
	s_waitcnt lgkmcnt(1)
	v_mfma_f32_32x32x16_bf16 v[80:95], v[240:243], v[104:107], v[80:95]
	ds_read_b128 v[240:243], v187 offset:40960
	v_exp_f32_e32 v223, v223
	v_pk_add_f32 v[170:171], v[170:171], v[220:221]
	v_exp_f32_e32 v224, v224
	v_exp_f32_e32 v225, v225
	s_waitcnt lgkmcnt(1)
	v_mfma_f32_32x32x16_bf16 v[64:79], v[236:239], v[108:111], v[64:79]
	ds_read_b128 v[236:239], v188 offset:32768
	v_pk_add_f32 v[170:171], v[170:171], v[222:223]
	v_exp_f32_e32 v226, v226
	v_exp_f32_e32 v227, v227
	s_waitcnt lgkmcnt(1)
	v_mfma_f32_32x32x16_bf16 v[80:95], v[240:243], v[108:111], v[80:95]
	ds_read_b128 v[240:243], v188 offset:40960
	v_pk_add_f32 v[170:171], v[170:171], v[224:225]
	v_exp_f32_e32 v228, v228
	v_exp_f32_e32 v229, v229
	v_pk_add_f32 v[170:171], v[170:171], v[226:227]
	s_waitcnt lgkmcnt(1)
	v_mfma_f32_32x32x16_bf16 v[64:79], v[236:239], v[112:115], v[64:79]
	ds_read_b128 v[236:239], v189 offset:32768
	v_exp_f32_e32 v230, v230
	v_exp_f32_e32 v231, v231
	v_pk_add_f32 v[170:171], v[170:171], v[228:229]
	v_exp_f32_e32 v232, v232
	s_waitcnt lgkmcnt(1)
	v_mfma_f32_32x32x16_bf16 v[80:95], v[240:243], v[112:115], v[80:95]
	ds_read_b128 v[240:243], v189 offset:40960
	v_exp_f32_e32 v233, v233
	v_pk_add_f32 v[170:171], v[170:171], v[230:231]
	v_exp_f32_e32 v234, v234
	s_waitcnt lgkmcnt(1)
	v_mfma_f32_32x32x16_bf16 v[64:79], v[236:239], v[116:119], v[64:79]
	v_xor_b32_e32 v186, 0x80, v186
	v_xor_b32_e32 v187, 0x80, v187
	v_xor_b32_e32 v188, 0x80, v188
	v_xor_b32_e32 v189, 0x80, v189
	ds_read_b128 v[236:239], v186 offset:32768
	v_exp_f32_e32 v235, v235
	v_pk_add_f32 v[170:171], v[170:171], v[232:233]
	s_nop 0
	v_pk_add_f32 v[170:171], v[170:171], v[234:235]
	s_waitcnt lgkmcnt(1)
	v_mfma_f32_32x32x16_bf16 v[80:95], v[240:243], v[116:119], v[80:95]
	ds_read_b128 v[240:243], v186 offset:40960
	v_add_f32_e32 v249, v170, v171
	v_mov_b32_e32 v170, v249
	s_nop 1
	s_waitcnt lgkmcnt(1)
	v_mfma_f32_32x32x16_bf16 v[64:79], v[236:239], v[120:123], v[64:79]
	ds_read_b128 v[236:239], v187 offset:32768
	v_permlane32_swap_b32_e32 v249, v170
	v_cvt_pk_bf16_f32 v204, v204, v205
	v_cvt_pk_bf16_f32 v205, v206, v207
	v_cvt_pk_bf16_f32 v206, v208, v209
	s_waitcnt lgkmcnt(1)
	v_mfma_f32_32x32x16_bf16 v[80:95], v[240:243], v[120:123], v[80:95]
	ds_read_b128 v[240:243], v187 offset:40960
	v_cvt_pk_bf16_f32 v207, v210, v211
	v_cvt_pk_bf16_f32 v208, v212, v213
	v_cvt_pk_bf16_f32 v209, v214, v215
	s_waitcnt lgkmcnt(1)
	v_mfma_f32_32x32x16_bf16 v[64:79], v[236:239], v[124:127], v[64:79]
	ds_read_b128 v[236:239], v188 offset:32768
	v_cvt_pk_bf16_f32 v210, v216, v217
	v_cvt_pk_bf16_f32 v211, v218, v219
	v_cvt_pk_bf16_f32 v212, v220, v221
	v_cvt_pk_bf16_f32 v213, v222, v223
	s_waitcnt lgkmcnt(1)
	v_mfma_f32_32x32x16_bf16 v[80:95], v[240:243], v[124:127], v[80:95]
	ds_read_b128 v[240:243], v188 offset:40960
	v_cvt_pk_bf16_f32 v214, v224, v225
	v_cvt_pk_bf16_f32 v215, v226, v227
	v_cvt_pk_bf16_f32 v216, v228, v229
	s_waitcnt lgkmcnt(1)
	v_mfma_f32_32x32x16_bf16 v[64:79], v[236:239], v[128:131], v[64:79]
	ds_read_b128 v[236:239], v189 offset:32768
	v_cvt_pk_bf16_f32 v217, v230, v231
	v_cvt_pk_bf16_f32 v218, v232, v233
	v_cvt_pk_bf16_f32 v219, v234, v235
	v_permlane32_swap_b32_e32 v204, v206
	s_waitcnt lgkmcnt(1)
	v_mfma_f32_32x32x16_bf16 v[80:95], v[240:243], v[128:131], v[80:95]
	ds_read_b128 v[240:243], v189 offset:40960
	v_permlane32_swap_b32_e32 v205, v207
	v_permlane32_swap_b32_e32 v208, v210
	v_permlane32_swap_b32_e32 v209, v211
	v_permlane32_swap_b32_e32 v212, v214
	s_waitcnt lgkmcnt(1)
	v_mfma_f32_32x32x16_bf16 v[64:79], v[236:239], v[132:135], v[64:79]
	v_permlane32_swap_b32_e32 v213, v215
	v_permlane32_swap_b32_e32 v216, v218
	v_permlane32_swap_b32_e32 v217, v219
	s_waitcnt lgkmcnt(0)
	v_mfma_f32_32x32x16_bf16 v[80:95], v[240:243], v[132:135], v[80:95]
	v_add_f32_e32 v171, v249, v170
	v_fmac_f32_e32 v171, v185, v202
	v_mov_b32_e32 v185, v171
	s_waitcnt vmcnt(0)
	s_and_b64 vcc, exec, s[34:35]
	s_cbranch_vccz .Lat_nwo
	v_add_u32_e32 v200, s8, v180
	v_add_u32_e32 v201, s8, v181
	ds_write_b128 v200, v[96:99]
	ds_write_b128 v201, v[100:103]
	ds_write_b128 v182, v[136:139] offset:49152
	ds_write_b128 v182, v[140:143] offset:57344
